# attn: V tile staged row-major with 4 dwordx4 loads per lane (no register transpose), PV A-operand via ds_read_b64_tr_b16 with XOR-swizzled conflict-free layout; epilogue stores 8B per value tile
# baseline (speedup 1.0000x reference)
.LBB0_248:
	ds_bpermute_b32 v0, v159, v222
	s_lshl_b32 s0, s14, 14
	s_add_u32 s0, s0, s15
	s_addc_u32 s8, 0, s16
	s_ashr_i32 s9, s18, 31
	s_waitcnt lgkmcnt(0)
	v_add_f32_e32 v2, v222, v0
	ds_bpermute_b32 v3, v160, v2
	s_add_u32 s0, s0, s18
	s_addc_u32 s8, s8, s9
	v_or_b32_e32 v0, s0, v165
	v_mov_b32_e32 v1, s8
	s_waitcnt lgkmcnt(0)
	v_add_f32_e32 v2, v2, v3
	v_rcp_f32_e32 v4, v2
	v_lshlrev_b64 v[0:1], 12, v[0:1]
	v_lshl_add_u64 v[0:1], s[6:7], 0, v[0:1]
	s_lshl_b32 s0, s13, 1
	v_lshl_add_u64 v[0:1], v[0:1], 0, s[0:1]
	v_mov_b32_e32 v64, v158
	v_lshl_add_u64 v[6:7], v[0:1], 0, v[64:65]
	v_pk_mul_f32 v[0:1], v[96:97], v[4:5] op_sel_hi:[1,0]
	v_pk_mul_f32 v[2:3], v[98:99], v[4:5] op_sel_hi:[1,0]
	v_cvt_pk_bf16_f32 v0, v0, v1
	v_cvt_pk_bf16_f32 v1, v2, v3
	global_store_dwordx2 v[6:7], v[0:1], off offset:0 nt
	s_add_i32 s12, s12, s42
	s_add_i32 s10, s10, s11
	v_pk_mul_f32 v[8:9], v[88:89], v[4:5] op_sel_hi:[1,0]
	v_pk_mul_f32 v[10:11], v[90:91], v[4:5] op_sel_hi:[1,0]
	v_cvt_pk_bf16_f32 v8, v8, v9
	v_cvt_pk_bf16_f32 v9, v10, v11
	global_store_dwordx2 v[6:7], v[8:9], off offset:32 nt
	v_pk_mul_f32 v[0:1], v[80:81], v[4:5] op_sel_hi:[1,0]
	v_pk_mul_f32 v[2:3], v[82:83], v[4:5] op_sel_hi:[1,0]
	v_cvt_pk_bf16_f32 v0, v0, v1
	v_cvt_pk_bf16_f32 v1, v2, v3
	global_store_dwordx2 v[6:7], v[0:1], off offset:64 nt
	v_pk_mul_f32 v[8:9], v[72:73], v[4:5] op_sel_hi:[1,0]
	v_pk_mul_f32 v[10:11], v[74:75], v[4:5] op_sel_hi:[1,0]
	v_cvt_pk_bf16_f32 v8, v8, v9
	v_cvt_pk_bf16_f32 v9, v10, v11
	global_store_dwordx2 v[6:7], v[8:9], off offset:96 nt
	v_pk_mul_f32 v[0:1], v[56:57], v[4:5] op_sel_hi:[1,0]
	v_pk_mul_f32 v[2:3], v[58:59], v[4:5] op_sel_hi:[1,0]
	v_cvt_pk_bf16_f32 v0, v0, v1
	v_cvt_pk_bf16_f32 v1, v2, v3
	global_store_dwordx2 v[6:7], v[0:1], off offset:128 nt
	v_pk_mul_f32 v[8:9], v[48:49], v[4:5] op_sel_hi:[1,0]
	v_pk_mul_f32 v[10:11], v[50:51], v[4:5] op_sel_hi:[1,0]
	v_cvt_pk_bf16_f32 v8, v8, v9
	v_cvt_pk_bf16_f32 v9, v10, v11
	global_store_dwordx2 v[6:7], v[8:9], off offset:160 nt
	v_pk_mul_f32 v[0:1], v[40:41], v[4:5] op_sel_hi:[1,0]
	v_pk_mul_f32 v[2:3], v[42:43], v[4:5] op_sel_hi:[1,0]
	v_cvt_pk_bf16_f32 v0, v0, v1
	v_cvt_pk_bf16_f32 v1, v2, v3
	global_store_dwordx2 v[6:7], v[0:1], off offset:192 nt
	v_pk_mul_f32 v[8:9], v[32:33], v[4:5] op_sel_hi:[1,0]
	v_pk_mul_f32 v[10:11], v[34:35], v[4:5] op_sel_hi:[1,0]
	v_cvt_pk_bf16_f32 v8, v8, v9
	v_cvt_pk_bf16_f32 v9, v10, v11
	global_store_dwordx2 v[6:7], v[8:9], off offset:224 nt
	v_pk_mul_f32 v[0:1], v[92:93], v[4:5] op_sel_hi:[1,0]
	v_pk_mul_f32 v[2:3], v[94:95], v[4:5] op_sel_hi:[1,0]
	v_cvt_pk_bf16_f32 v0, v0, v1
	v_cvt_pk_bf16_f32 v1, v2, v3
	global_store_dwordx2 v[6:7], v[0:1], off offset:256 nt
	v_pk_mul_f32 v[8:9], v[84:85], v[4:5] op_sel_hi:[1,0]
	v_pk_mul_f32 v[10:11], v[86:87], v[4:5] op_sel_hi:[1,0]
	v_cvt_pk_bf16_f32 v8, v8, v9
	v_cvt_pk_bf16_f32 v9, v10, v11
	global_store_dwordx2 v[6:7], v[8:9], off offset:288 nt
	v_pk_mul_f32 v[0:1], v[76:77], v[4:5] op_sel_hi:[1,0]
	v_pk_mul_f32 v[2:3], v[78:79], v[4:5] op_sel_hi:[1,0]
	v_cvt_pk_bf16_f32 v0, v0, v1
	v_cvt_pk_bf16_f32 v1, v2, v3
	global_store_dwordx2 v[6:7], v[0:1], off offset:320 nt
	v_pk_mul_f32 v[8:9], v[68:69], v[4:5] op_sel_hi:[1,0]
	v_pk_mul_f32 v[10:11], v[70:71], v[4:5] op_sel_hi:[1,0]
	v_cvt_pk_bf16_f32 v8, v8, v9
	v_cvt_pk_bf16_f32 v9, v10, v11
	global_store_dwordx2 v[6:7], v[8:9], off offset:352 nt
	v_pk_mul_f32 v[0:1], v[60:61], v[4:5] op_sel_hi:[1,0]
	v_pk_mul_f32 v[2:3], v[62:63], v[4:5] op_sel_hi:[1,0]
	v_cvt_pk_bf16_f32 v0, v0, v1
	v_cvt_pk_bf16_f32 v1, v2, v3
	global_store_dwordx2 v[6:7], v[0:1], off offset:384 nt
	v_pk_mul_f32 v[8:9], v[52:53], v[4:5] op_sel_hi:[1,0]
	v_pk_mul_f32 v[10:11], v[54:55], v[4:5] op_sel_hi:[1,0]
	v_cvt_pk_bf16_f32 v8, v8, v9
	v_cvt_pk_bf16_f32 v9, v10, v11
	global_store_dwordx2 v[6:7], v[8:9], off offset:416 nt
	v_pk_mul_f32 v[0:1], v[44:45], v[4:5] op_sel_hi:[1,0]
	v_pk_mul_f32 v[2:3], v[46:47], v[4:5] op_sel_hi:[1,0]
	v_cvt_pk_bf16_f32 v0, v0, v1
	v_cvt_pk_bf16_f32 v1, v2, v3
	global_store_dwordx2 v[6:7], v[0:1], off offset:448 nt
	v_pk_mul_f32 v[8:9], v[36:37], v[4:5] op_sel_hi:[1,0]
	v_pk_mul_f32 v[10:11], v[38:39], v[4:5] op_sel_hi:[1,0]
	v_cvt_pk_bf16_f32 v8, v8, v9
	v_cvt_pk_bf16_f32 v9, v10, v11
	global_store_dwordx2 v[6:7], v[8:9], off offset:480 nt
	s_cmpk_gt_i32 s12, 0x7ff
	s_nop 0
	s_cbranch_scc1 .LBB0_262

.LBB0_251:
	s_or_b64 exec, exec, s[8:9]
	s_and_b32 s0, s10, 0x780
	s_sub_i32 s17, s3, s0
	s_lshl_b32 s0, s12, 3
	s_and_b32 s15, s0, 0xfffff800
	s_bfe_u32 s14, s12, 0x10004
	s_ashr_i32 s16, s15, 31
	s_mul_i32 s8, s15, 0xa080
	s_mul_hi_i32 s0, s15, 0xa080
	s_add_u32 s9, s4, s8
	s_addc_u32 s18, s5, s0
	s_lshl_b32 s13, s19, 8
	s_lshl_b32 s0, s19, 9
	s_lshl_b32 s8, s14, 8
	s_add_u32 s20, s9, s0
	s_addc_u32 s21, s18, 0
	s_add_u32 s22, s20, s8
	v_lshlrev_b32_e32 v0, 4, v16
	s_addc_u32 s23, s21, 0
	s_add_u32 s24, s22, 0x7000
	s_addc_u32 s25, s23, 0
	s_add_u32 s26, s20, 0x8000
	s_addc_u32 s27, s21, 0
	v_and_b32_e32 v26, 0xf0, v0
	v_mov_b32_e32 v27, v65
	v_lshl_add_u64 v[0:1], s[22:23], 0, v[26:27]
	s_mov_b64 s[22:23], 0x7000
	v_lshl_add_u64 v[154:155], v[0:1], 0, s[22:23]
	v_ashrrev_i32_e32 v161, 4, v16
	v_add_u32_e32 v27, 0x200, v16
	v_mad_i64_i32 v[0:1], s[22:23], v161, s69, v[154:155]
	v_ashrrev_i32_e32 v162, 4, v27
	v_mad_i64_i32 v[2:3], s[22:23], v162, s69, v[154:155]
	global_load_dwordx4 v[18:21], v[0:1], off
	global_load_dwordx4 v[22:25], v[2:3], off
	v_and_b32_e32 v246, 15, v190
	v_mul_u32_u24_e32 v247, 0xa080, v161
	v_lshl_add_u32 v246, v246, 4, v247
	v_add_u32_e32 v247, 0x141000, v246
	v_lshrrev_b32_e32 v239, 5, v190
	v_and_b32_e32 v169, 7, v239
	v_lshlrev_b32_e32 v169, 1, v169
	v_and_b32_e32 v172, 31, v190
	v_xor_b32_e32 v169, v169, v172
	v_mul_u32_u24_e32 v239, 0xa080, v239
	v_lshl_add_u32 v239, v169, 4, v239
	v_lshlrev_b32_e32 v169, 4, v190
	v_add_u32_e32 v169, 0x8800, v169
	v_lshrrev_b32_e32 v171, 2, v185
	v_and_b32_e32 v220, 3, v185
	v_lshlrev_b32_e32 v220, 3, v220
	v_lshl_add_u32 v220, v171, 9, v220
	v_add_u32_e32 v220, 0x8800, v220
	v_and_b32_e32 v171, 7, v171
	v_xor_b32_e32 v172, 0, v171
	v_lshl_add_u32 v172, v172, 5, v220
	v_xor_b32_e32 v175, 1, v171
	v_lshl_add_u32 v175, v175, 5, v220
	v_xor_b32_e32 v176, 2, v171
	v_lshl_add_u32 v176, v176, 5, v220
	v_xor_b32_e32 v181, 3, v171
	v_lshl_add_u32 v181, v181, 5, v220
	v_xor_b32_e32 v218, 4, v171
	v_lshl_add_u32 v218, v218, 5, v220
	v_xor_b32_e32 v219, 5, v171
	v_lshl_add_u32 v219, v219, 5, v220
	v_xor_b32_e32 v27, 7, v171
	v_xor_b32_e32 v171, 6, v171
	v_lshl_add_u32 v171, v171, 5, v220
	v_lshl_add_u32 v27, v27, 5, v220
	v_mov_b32_e32 v220, v171
	v_mov_b32_e32 v171, v27
	s_mov_b32 s29, 0x0
	s_add_u32 s72, s24, s29
	s_addc_u32 s73, s25, 0
	s_add_u32 s74, s26, s29
	s_addc_u32 s75, s27, 0
	s_add_u32 s76, s74, 0xa0800
	s_addc_u32 s77, s75, 0
	s_add_u32 s78, s76, 0xa0800
	s_addc_u32 s79, s77, 0
	s_add_u32 s80, s78, 0xa0800
	s_addc_u32 s81, s79, 0
	s_waitcnt vmcnt(2)
	global_load_dwordx4 v[206:209], v239, s[74:75]
	global_load_dwordx4 v[210:213], v239, s[76:77]
	global_load_dwordx4 v[214:217], v239, s[78:79]
	global_load_dwordx4 v[248:251], v239, s[80:81]
	s_lshl_b32 s18, s12, 7
	s_and_b32 s18, s18, 0x780
	s_add_i32 s18, s18, s2
	s_lshl_b32 s19, s19, 2
	v_readlane_b32 s52, v252, 25
	v_and_b32_e32 v165, 15, v16
	v_readlane_b32 s60, v252, 33
	v_readlane_b32 s61, v252, 34
	s_mov_b32 s9, s1
	v_bfe_u32 v43, v16, 4, 2
	v_lshlrev_b32_e32 v64, 4, v43
	v_add_u32_e32 v26, 0, v26
	v_lshlrev_b32_e32 v158, 3, v43
	v_mov_b32_e32 v0, s19
	s_add_i32 s19, s18, s15
	global_load_dword v44, v0, s[60:61] offset:480
	global_load_dword v45, v0, s[60:61] offset:992
	v_or_b32_e32 v2, s19, v165
	v_mov_b64_e32 v[0:1], s[4:5]
	v_mad_i64_i32 v[0:1], s[20:21], v2, s69, v[0:1]
	v_lshl_add_u64 v[0:1], v[0:1], 0, s[0:1]
	v_lshl_add_u64 v[0:1], v[0:1], 0, s[8:9]
	v_lshl_add_u64 v[0:1], v[0:1], 0, v[64:65]
	s_movk_i32 s0, 0x6000
	v_add_co_u32_e32 v8, vcc, s0, v0
	s_movk_i32 s0, 0x110
	s_mov_b64 s[8:9], 0x6000
	v_mul_lo_u32 v46, v161, s0
	v_lshl_add_u64 v[12:13], v[0:1], 0, s[8:9]
	v_addc_co_u32_e32 v9, vcc, 0, v1, vcc
	v_add_u32_e32 v166, v26, v46
	global_load_dwordx4 v[0:3], v[12:13], off offset:64
	global_load_dwordx4 v[4:7], v[12:13], off offset:128
	s_nop 0
	global_load_dwordx4 v[8:11], v[8:9], off
	s_nop 0
	global_load_dwordx4 v[12:15], v[12:13], off offset:192
	s_waitcnt vmcnt(0)
	ds_write_b128 v166, v[18:21]
	v_mul_lo_u32 v18, v162, s0
	v_add_u32_e32 v167, v26, v18
	s_waitcnt vmcnt(22)
	ds_write_b128 v167, v[22:25]
	s_cmp_lg_u32 0, -1
	v_mov_b32_e32 v66, v65
	v_mov_b32_e32 v67, v65
	v_mov_b32_e32 v221, 0xf149f2ca
	v_mov_b32_e32 v222, 0
	v_readlane_b32 s53, v252, 26
	v_readlane_b32 s54, v252, 27
	v_readlane_b32 s55, v252, 28
	ds_write_b128 v169, v[206:209] offset:0
	ds_write_b128 v169, v[210:213] offset:8192
	ds_write_b128 v169, v[214:217] offset:16384
	ds_write_b128 v169, v[248:251] offset:24576
	s_waitcnt lgkmcnt(0)
	s_barrier
	s_mov_b32 s29, 0x282000
	s_add_u32 s72, s24, s29
	s_addc_u32 s73, s25, 0
	s_add_u32 s74, s26, s29
	s_addc_u32 s75, s27, 0
	s_add_u32 s76, s74, 0xa0800
	s_addc_u32 s77, s75, 0
	s_add_u32 s78, s76, 0xa0800
	s_addc_u32 s79, s77, 0
	s_add_u32 s80, s78, 0xa0800
	s_addc_u32 s81, s79, 0
	global_load_dwordx4 v[194:197], v239, s[74:75]
	global_load_dwordx4 v[198:201], v239, s[76:77]
	global_load_dwordx4 v[202:205], v239, s[78:79]
	global_load_dwordx4 v[242:245], v239, s[80:81]
	global_load_dwordx4 v[16:19], v246, s[72:73]
	global_load_dwordx4 v[20:23], v247, s[72:73]
	v_readlane_b32 s8, v254, 60
	s_waitcnt vmcnt(15)
	v_mul_f32_e32 v173, 0x413504f3, v44
	s_waitcnt vmcnt(14)
	v_mul_f32_e32 v174, 0x413504f3, v45
	v_readlane_b32 s56, v252, 29
	v_readlane_b32 s57, v252, 30
	v_readlane_b32 s58, v252, 31
	v_readlane_b32 s59, v252, 32
	v_mad_u32_u24 v27, v165, s0, v64
	s_cselect_b32 s0, 0, 0
	s_cmp_lg_u32 s8, -1
	s_cselect_b32 s8, s8, 0
	v_mov_b32_e32 v64, v65
	v_lshlrev_b32_e32 v30, 2, v43
	v_add_u32_e32 v177, s0, v27
	s_add_i32 s8, s0, 0x4400
	s_add_i32 s0, s0, 0x11800
	v_mov_b64_e32 v[36:37], v[64:65]
	v_mov_b64_e32 v[44:45], v[64:65]
	v_mov_b64_e32 v[52:53], v[64:65]
	v_mov_b64_e32 v[60:61], v[64:65]
	v_mov_b64_e32 v[70:71], v[66:67]
	v_mov_b64_e32 v[78:79], v[66:67]
	v_mov_b64_e32 v[86:87], v[66:67]
	v_mov_b64_e32 v[94:95], v[66:67]
	v_mov_b64_e32 v[32:33], v[64:65]
	v_mov_b64_e32 v[40:41], v[64:65]
	v_mov_b64_e32 v[48:49], v[64:65]
	v_mov_b64_e32 v[56:57], v[64:65]
	v_mov_b64_e32 v[74:75], v[66:67]
	v_mov_b64_e32 v[82:83], v[66:67]
	v_mov_b64_e32 v[90:91], v[66:67]
	v_mov_b64_e32 v[98:99], v[66:67]
	s_mov_b32 s29, 0x504000
	s_add_u32 s72, s24, s29
	s_addc_u32 s73, s25, 0
	s_add_u32 s74, s26, s29
	s_addc_u32 s75, s27, 0
	s_add_u32 s76, s74, 0xa0800
	s_addc_u32 s77, s75, 0
	s_add_u32 s78, s76, 0xa0800
	s_addc_u32 s79, s77, 0
	s_add_u32 s80, s78, 0xa0800
	s_addc_u32 s81, s79, 0
	v_add_u32_e32 v191, s8, v27
	v_sub_u32_e32 v193, v30, v165
	s_mov_b32 s0, -2
	v_mov_b64_e32 v[38:39], v[66:67]
	v_mov_b64_e32 v[46:47], v[66:67]
	v_mov_b64_e32 v[54:55], v[66:67]
	v_mov_b64_e32 v[62:63], v[66:67]
	v_mov_b64_e32 v[68:69], v[64:65]
	v_mov_b64_e32 v[76:77], v[64:65]
	v_mov_b64_e32 v[84:85], v[64:65]
	v_mov_b64_e32 v[92:93], v[64:65]
	v_mov_b64_e32 v[34:35], v[66:67]
	v_mov_b64_e32 v[42:43], v[66:67]
	v_mov_b64_e32 v[50:51], v[66:67]
	v_mov_b64_e32 v[58:59], v[66:67]
	v_mov_b64_e32 v[72:73], v[64:65]
	v_mov_b64_e32 v[80:81], v[64:65]
	v_mov_b64_e32 v[88:89], v[64:65]
	v_mov_b64_e32 v[96:97], v[64:65]
	v_readlane_b32 s62, v252, 35
	v_readlane_b32 s63, v252, 36
	v_readlane_b32 s64, v252, 37
	v_readlane_b32 s65, v252, 38
	v_readlane_b32 s66, v252, 39
	v_readlane_b32 s67, v252, 40
.LBB0_252:
	ds_read_b128 v[100:103], v177 offset:0
	ds_read_b128 v[104:107], v177 offset:64
	ds_read_b128 v[108:111], v177 offset:0x80
	ds_read_b128 v[112:115], v177 offset:0xc0
	ds_read_b128 v[116:119], v177 offset:0x1100
	ds_read_b128 v[120:123], v177 offset:0x1140
	ds_read_b128 v[124:127], v177 offset:0x1180
	ds_read_b128 v[128:131], v177 offset:0x11c0
	global_load_dwordx4 v[206:209], v239, s[74:75]
	global_load_dwordx4 v[210:213], v239, s[76:77]
	global_load_dwordx4 v[214:217], v239, s[78:79]
	global_load_dwordx4 v[248:251], v239, s[80:81]
	global_load_dwordx4 v[24:27], v246, s[72:73]
	global_load_dwordx4 v[28:31], v247, s[72:73]
	s_waitcnt lgkmcnt(0)
	s_waitcnt vmcnt(37)
	v_mfma_f32_16x16x32_bf16 v[100:103], v[100:103], v[8:11], 0
	v_mfma_f32_16x16x32_bf16 v[116:119], v[116:119], v[8:11], 0
	v_mfma_f32_16x16x32_bf16 v[100:103], v[104:107], v[0:3], v[100:103]
	v_mfma_f32_16x16x32_bf16 v[104:107], v[120:123], v[0:3], v[116:119]
	v_mfma_f32_16x16x32_bf16 v[100:103], v[108:111], v[4:7], v[100:103]
	v_mfma_f32_16x16x32_bf16 v[108:111], v[124:127], v[4:7], v[104:107]
	s_waitcnt vmcnt(36)
	v_mfma_f32_16x16x32_bf16 v[104:107], v[112:115], v[12:15], v[100:103]
	v_mfma_f32_16x16x32_bf16 v[100:103], v[128:131], v[12:15], v[108:111]
	ds_read_b128 v[108:111], v177 offset:0x2200
	ds_read_b128 v[112:115], v177 offset:0x2240
	ds_read_b128 v[116:119], v177 offset:0x2280
	ds_read_b128 v[120:123], v177 offset:0x22c0
	ds_read_b128 v[124:127], v177 offset:0x3300
	ds_read_b128 v[128:131], v177 offset:0x3340
	ds_read_b128 v[132:135], v177 offset:0x3380
	ds_read_b128 v[136:139], v177 offset:0x33c0
	s_waitcnt lgkmcnt(0)
	s_nop 4
	v_mfma_f32_16x16x32_bf16 v[108:111], v[108:111], v[8:11], 0
	s_add_i32 s8, s17, 0xffffff56
	s_cmp_lt_u32 s8, 0xfffffefd
	v_mfma_f32_16x16x32_bf16 v[108:111], v[112:115], v[0:3], v[108:111]
	v_mfma_f32_16x16x32_bf16 v[124:127], v[124:127], v[8:11], 0
	v_mfma_f32_16x16x32_bf16 v[108:111], v[116:119], v[4:7], v[108:111]
	ds_read_b64_tr_b16 v[116:117], v172 offset:0
	ds_read_b64_tr_b16 v[118:119], v172 offset:8192
	v_mfma_f32_16x16x32_bf16 v[112:115], v[128:131], v[0:3], v[124:127]
	v_mfma_f32_16x16x32_bf16 v[128:131], v[120:123], v[12:15], v[108:111]
	ds_read_b64_tr_b16 v[108:109], v172 offset:16384
	ds_read_b64_tr_b16 v[110:111], v172 offset:24576
	ds_read_b64_tr_b16 v[120:121], v175 offset:0
	v_mfma_f32_16x16x32_bf16 v[112:115], v[132:135], v[4:7], v[112:115]
	ds_read_b64_tr_b16 v[122:123], v175 offset:8192
	ds_read_b64_tr_b16 v[124:125], v175 offset:16384
	ds_read_b64_tr_b16 v[126:127], v175 offset:24576
	v_mfma_f32_16x16x32_bf16 v[112:115], v[136:139], v[12:15], v[112:115]
	ds_read_b64_tr_b16 v[136:137], v176 offset:0
	ds_read_b64_tr_b16 v[138:139], v176 offset:8192
	ds_read_b64_tr_b16 v[132:133], v176 offset:16384
	ds_read_b64_tr_b16 v[134:135], v176 offset:24576
	ds_read_b64_tr_b16 v[140:141], v181 offset:0
	ds_read_b64_tr_b16 v[142:143], v181 offset:8192
	ds_read_b64_tr_b16 v[144:145], v181 offset:16384
	ds_read_b64_tr_b16 v[146:147], v181 offset:24576
	s_cbranch_scc1 .LBB0_254
	v_add3_u32 v152, v193, s17, 64
	v_max_i32_e32 v67, -1, v152
	v_add_u32_e32 v67, 1, v67
	v_med3_i32 v66, v152, 0, v188
	s_add_i32 s8, 0, 0x1a800
	v_min_u32_e32 v67, 0x100, v67
	v_lshl_add_u32 v66, v66, 2, s8
	v_lshl_add_u32 v67, v67, 2, s8
	ds_read_b32 v66, v66
	ds_read_b32 v67, v67
	v_max_i32_e32 v153, -2, v152
	v_add_u32_e32 v153, 2, v153
	v_min_u32_e32 v153, 0x100, v153
	v_lshl_add_u32 v153, v153, 2, s8
	ds_read_b32 v224, v153
	v_max_i32_e32 v153, -3, v152
	s_waitcnt lgkmcnt(1)
	v_pk_add_f32 v[104:105], v[104:105], v[66:67]
	v_max_i32_e32 v66, -16, v152
	v_max_i32_e32 v67, 0xffffffef, v152
	v_add_u32_e32 v153, 3, v153
	v_add_u32_e32 v66, 16, v66
	v_add_u32_e32 v67, 17, v67
	v_min_u32_e32 v153, 0x100, v153
	v_min_u32_e32 v66, 0x100, v66
	v_min_u32_e32 v67, 0x100, v67
	v_lshl_add_u32 v153, v153, 2, s8
	v_lshl_add_u32 v66, v66, 2, s8
	v_lshl_add_u32 v67, v67, 2, s8
	ds_read_b32 v225, v153
	ds_read_b32 v66, v66
	ds_read_b32 v67, v67
	v_max_i32_e32 v153, 0xffffffee, v152
	v_add_u32_e32 v153, 18, v153
	v_min_u32_e32 v153, 0x100, v153
	v_lshl_add_u32 v153, v153, 2, s8
	s_waitcnt lgkmcnt(0)
	v_pk_add_f32 v[100:101], v[100:101], v[66:67]
	v_max_i32_e32 v66, 0xffffffe0, v152
	v_max_i32_e32 v67, 0xffffffdf, v152
	v_add_u32_e32 v66, 32, v66
	v_add_u32_e32 v67, 33, v67
	v_min_u32_e32 v66, 0x100, v66
	v_min_u32_e32 v67, 0x100, v67
	v_lshl_add_u32 v66, v66, 2, s8
	v_lshl_add_u32 v67, v67, 2, s8
	v_pk_add_f32 v[106:107], v[106:107], v[224:225]
	ds_read_b32 v224, v153
	ds_read_b32 v66, v66
	ds_read_b32 v67, v67
	v_max_i32_e32 v153, 0xffffffed, v152
	v_add_u32_e32 v153, 19, v153
	v_min_u32_e32 v153, 0x100, v153
	v_lshl_add_u32 v153, v153, 2, s8
	ds_read_b32 v225, v153
	v_max_i32_e32 v153, 0xffffffde, v152
	v_add_u32_e32 v153, 34, v153
	v_min_u32_e32 v153, 0x100, v153
	v_lshl_add_u32 v153, v153, 2, s8
	s_waitcnt lgkmcnt(0)
	v_pk_add_f32 v[102:103], v[102:103], v[224:225]
	ds_read_b32 v224, v153
	v_max_i32_e32 v153, 0xffffffdd, v152
	v_add_u32_e32 v153, 35, v153
	v_min_u32_e32 v153, 0x100, v153
	v_lshl_add_u32 v153, v153, 2, s8
	ds_read_b32 v225, v153
	v_pk_add_f32 v[128:129], v[128:129], v[66:67]
	v_max_i32_e32 v66, 0xffffffd0, v152
	v_max_i32_e32 v67, 0xffffffcf, v152
	v_max_i32_e32 v153, 0xffffffce, v152
	v_max_i32_e32 v152, 0xffffffcd, v152
	v_add_u32_e32 v66, 48, v66
	v_add_u32_e32 v67, 49, v67
	v_add_u32_e32 v153, 50, v153
	v_add_u32_e32 v152, 51, v152
	v_min_u32_e32 v66, 0x100, v66
	v_min_u32_e32 v67, 0x100, v67
	v_min_u32_e32 v153, 0x100, v153
	v_min_u32_e32 v152, 0x100, v152
	v_lshl_add_u32 v66, v66, 2, s8
	v_lshl_add_u32 v67, v67, 2, s8
	v_lshl_add_u32 v153, v153, 2, s8
	v_lshl_add_u32 v152, v152, 2, s8
	s_waitcnt lgkmcnt(0)
	v_pk_add_f32 v[130:131], v[130:131], v[224:225]
	ds_read_b32 v66, v66
	ds_read_b32 v67, v67
	ds_read_b32 v224, v153
	ds_read_b32 v225, v152
	s_waitcnt lgkmcnt(2)
	v_pk_add_f32 v[112:113], v[112:113], v[66:67]
	s_waitcnt lgkmcnt(0)
	v_pk_add_f32 v[114:115], v[114:115], v[224:225]

.LBB0_256:
	v_sub_f32_e32 v66, v66, v221
	v_mul_f32_e32 v66, 0x3e0293ee, v66
	v_fmamk_f32 v67, v104, 0x3e0293ee, v66
	v_exp_f32_e32 v223, v67
	v_fmamk_f32 v67, v105, 0x3e0293ee, v66
	v_exp_f32_e32 v224, v67
	v_fmamk_f32 v67, v106, 0x3e0293ee, v66
	v_exp_f32_e32 v225, v67
	v_fmamk_f32 v67, v107, 0x3e0293ee, v66
	v_exp_f32_e32 v226, v67
	v_fmamk_f32 v67, v100, 0x3e0293ee, v66
	v_exp_f32_e32 v227, v67
	v_fmamk_f32 v67, v101, 0x3e0293ee, v66
	v_exp_f32_e32 v228, v67
	v_fmamk_f32 v67, v102, 0x3e0293ee, v66
	v_exp_f32_e32 v229, v67
	v_fmamk_f32 v67, v103, 0x3e0293ee, v66
	v_exp_f32_e32 v230, v67
	v_fmamk_f32 v67, v128, 0x3e0293ee, v66
	v_exp_f32_e32 v231, v67
	v_fmamk_f32 v67, v129, 0x3e0293ee, v66
	v_exp_f32_e32 v232, v67
	v_fmamk_f32 v67, v130, 0x3e0293ee, v66
	v_exp_f32_e32 v233, v67
	v_fmamk_f32 v67, v131, 0x3e0293ee, v66
	v_exp_f32_e32 v234, v67
	v_fmamk_f32 v67, v112, 0x3e0293ee, v66
	v_exp_f32_e32 v235, v67
	v_fmamk_f32 v67, v113, 0x3e0293ee, v66
	v_exp_f32_e32 v236, v67
	v_fmamk_f32 v67, v114, 0x3e0293ee, v66
	v_fmac_f32_e32 v66, 0x3e0293ee, v115
	v_exp_f32_e32 v237, v67
	v_exp_f32_e32 v238, v66
	s_waitcnt lgkmcnt(0)
	s_add_i32 s8, s0, 2
	v_cvt_pk_bf16_f32 v104, v223, v224
	v_cvt_pk_bf16_f32 v105, v225, v226
	v_cvt_pk_bf16_f32 v106, v227, v228
	v_cvt_pk_bf16_f32 v107, v229, v230
	v_cvt_pk_bf16_f32 v100, v231, v232
	v_cvt_pk_bf16_f32 v101, v233, v234
	v_cvt_pk_bf16_f32 v102, v235, v236
	v_cvt_pk_bf16_f32 v103, v237, v238
	v_mfma_f32_16x16x32_bf16 v[96:99], v[116:119], v[104:107], v[96:99]
	s_nop 0
	v_mfma_f32_16x16x32_bf16 v[96:99], v[108:111], v[100:103], v[96:99]
	ds_read_b64_tr_b16 v[108:109], v218 offset:0
	ds_read_b64_tr_b16 v[110:111], v218 offset:8192
	ds_read_b64_tr_b16 v[112:113], v218 offset:16384
	ds_read_b64_tr_b16 v[114:115], v218 offset:24576
	v_mfma_f32_16x16x32_bf16 v[88:91], v[120:123], v[104:107], v[88:91]
	ds_read_b64_tr_b16 v[116:117], v219 offset:0
	ds_read_b64_tr_b16 v[118:119], v219 offset:8192
	ds_read_b64_tr_b16 v[120:121], v219 offset:16384
	ds_read_b64_tr_b16 v[122:123], v219 offset:24576
	v_mfma_f32_16x16x32_bf16 v[80:83], v[136:139], v[104:107], v[80:83]
	v_mfma_f32_16x16x32_bf16 v[88:91], v[124:127], v[100:103], v[88:91]
	ds_read_b64_tr_b16 v[124:125], v220 offset:0
	ds_read_b64_tr_b16 v[126:127], v220 offset:8192
	ds_read_b64_tr_b16 v[128:129], v220 offset:16384
	v_mfma_f32_16x16x32_bf16 v[72:75], v[140:143], v[104:107], v[72:75]
	ds_read_b64_tr_b16 v[130:131], v220 offset:24576
	v_mfma_f32_16x16x32_bf16 v[80:83], v[132:135], v[100:103], v[80:83]
	ds_read_b64_tr_b16 v[132:133], v171 offset:0
	ds_read_b64_tr_b16 v[134:135], v171 offset:8192
	ds_read_b64_tr_b16 v[136:137], v171 offset:16384
	v_mfma_f32_16x16x32_bf16 v[72:75], v[144:147], v[100:103], v[72:75]
	ds_read_b64_tr_b16 v[138:139], v171 offset:24576
	s_waitcnt lgkmcnt(0)
	v_mfma_f32_16x16x32_bf16 v[56:59], v[108:111], v[104:107], v[56:59]
	ds_read_b64_tr_b16 v[108:109], v172 offset:256
	ds_read_b64_tr_b16 v[110:111], v172 offset:8448
	v_mfma_f32_16x16x32_bf16 v[48:51], v[116:119], v[104:107], v[48:51]
	v_mfma_f32_16x16x32_bf16 v[56:59], v[112:115], v[100:103], v[56:59]
	ds_read_b64_tr_b16 v[112:113], v172 offset:16640
	ds_read_b64_tr_b16 v[114:115], v172 offset:24832
	ds_read_b64_tr_b16 v[116:117], v175 offset:256
	ds_read_b64_tr_b16 v[118:119], v175 offset:8448
	v_mfma_f32_16x16x32_bf16 v[40:43], v[124:127], v[104:107], v[40:43]
	v_mfma_f32_16x16x32_bf16 v[48:51], v[120:123], v[100:103], v[48:51]
	ds_read_b64_tr_b16 v[120:121], v175 offset:16640
	ds_read_b64_tr_b16 v[122:123], v175 offset:24832
	ds_read_b64_tr_b16 v[124:125], v176 offset:256
	ds_read_b64_tr_b16 v[126:127], v176 offset:8448
	v_mfma_f32_16x16x32_bf16 v[32:35], v[132:135], v[104:107], v[32:35]
	v_mfma_f32_16x16x32_bf16 v[40:43], v[128:131], v[100:103], v[40:43]
	ds_read_b64_tr_b16 v[128:129], v176 offset:16640
	ds_read_b64_tr_b16 v[130:131], v176 offset:24832
	ds_read_b64_tr_b16 v[132:133], v181 offset:256
	ds_read_b64_tr_b16 v[134:135], v181 offset:8448
	v_mfma_f32_16x16x32_bf16 v[32:35], v[136:139], v[100:103], v[32:35]
	ds_read_b64_tr_b16 v[136:137], v181 offset:16640
	ds_read_b64_tr_b16 v[138:139], v181 offset:24832
	s_waitcnt lgkmcnt(0)
	v_mfma_f32_16x16x32_bf16 v[92:95], v[108:111], v[104:107], v[92:95]
	ds_read_b64_tr_b16 v[108:109], v218 offset:256
	ds_read_b64_tr_b16 v[110:111], v218 offset:8448
	v_mfma_f32_16x16x32_bf16 v[84:87], v[116:119], v[104:107], v[84:87]
	v_mfma_f32_16x16x32_bf16 v[92:95], v[112:115], v[100:103], v[92:95]
	ds_read_b64_tr_b16 v[112:113], v218 offset:16640
	ds_read_b64_tr_b16 v[114:115], v218 offset:24832
	ds_read_b64_tr_b16 v[116:117], v219 offset:256
	ds_read_b64_tr_b16 v[118:119], v219 offset:8448
	v_mfma_f32_16x16x32_bf16 v[76:79], v[124:127], v[104:107], v[76:79]
	v_mfma_f32_16x16x32_bf16 v[84:87], v[120:123], v[100:103], v[84:87]
	ds_read_b64_tr_b16 v[120:121], v219 offset:16640
	ds_read_b64_tr_b16 v[122:123], v219 offset:24832
	ds_read_b64_tr_b16 v[124:125], v220 offset:256
	ds_read_b64_tr_b16 v[126:127], v220 offset:8448
	v_mfma_f32_16x16x32_bf16 v[66:69], v[132:135], v[104:107], v[68:71]
	v_mfma_f32_16x16x32_bf16 v[76:79], v[128:131], v[100:103], v[76:79]
	ds_read_b64_tr_b16 v[128:129], v220 offset:16640
	ds_read_b64_tr_b16 v[130:131], v220 offset:24832
	ds_read_b64_tr_b16 v[132:133], v171 offset:256
	ds_read_b64_tr_b16 v[134:135], v171 offset:8448
	v_mfma_f32_16x16x32_bf16 v[66:69], v[136:139], v[100:103], v[66:69]
	ds_read_b64_tr_b16 v[136:137], v171 offset:16640
	ds_read_b64_tr_b16 v[138:139], v171 offset:24832
	s_waitcnt lgkmcnt(0)
	v_mfma_f32_16x16x32_bf16 v[60:63], v[108:111], v[104:107], v[60:63]
	v_mfma_f32_16x16x32_bf16 v[52:55], v[116:119], v[104:107], v[52:55]
	v_mfma_f32_16x16x32_bf16 v[44:47], v[124:127], v[104:107], v[44:47]
	v_mfma_f32_16x16x32_bf16 v[36:39], v[132:135], v[104:107], v[36:39]
	v_mfma_f32_16x16x32_bf16 v[60:63], v[112:115], v[100:103], v[60:63]
	v_mfma_f32_16x16x32_bf16 v[52:55], v[120:123], v[100:103], v[52:55]
	v_mfma_f32_16x16x32_bf16 v[44:47], v[128:131], v[100:103], v[44:47]
	v_mfma_f32_16x16x32_bf16 v[36:39], v[136:139], v[100:103], v[36:39]
	s_waitcnt vmcnt(6)
	ds_write_b128 v166, v[16:19] offset:17408
	ds_write_b128 v167, v[20:23] offset:17408
	ds_write_b128 v169, v[194:197] offset:36864
	ds_write_b128 v169, v[198:201] offset:45056
	ds_write_b128 v169, v[202:205] offset:53248
	ds_write_b128 v169, v[242:245] offset:61440
	s_min_u32 s9, s8, 28
	s_lshl_b32 s9, s9, 6
	s_addk_i32 s9, 0xc0
	s_mul_i32 s29, s9, 0xa080
	s_add_u32 s72, s24, s29
	s_addc_u32 s73, s25, 0
	s_add_u32 s74, s26, s29
	s_addc_u32 s75, s27, 0
	s_add_u32 s76, s74, 0xa0800
	s_addc_u32 s77, s75, 0
	s_add_u32 s78, s76, 0xa0800
	s_addc_u32 s79, s77, 0
	s_add_u32 s80, s78, 0xa0800
	s_addc_u32 s81, s79, 0
	s_waitcnt lgkmcnt(0)
	s_barrier
	ds_read_b128 v[100:103], v191 offset:0
	ds_read_b128 v[104:107], v191 offset:64
	ds_read_b128 v[108:111], v191 offset:0x80
	ds_read_b128 v[112:115], v191 offset:0xc0
	ds_read_b128 v[116:119], v191 offset:0x1100
	ds_read_b128 v[120:123], v191 offset:0x1140
	ds_read_b128 v[124:127], v191 offset:0x1180
	ds_read_b128 v[128:131], v191 offset:0x11c0
	global_load_dwordx4 v[194:197], v239, s[74:75]
	global_load_dwordx4 v[198:201], v239, s[76:77]
	global_load_dwordx4 v[202:205], v239, s[78:79]
	global_load_dwordx4 v[242:245], v239, s[80:81]
	global_load_dwordx4 v[16:19], v246, s[72:73]
	global_load_dwordx4 v[20:23], v247, s[72:73]
	s_waitcnt lgkmcnt(0)
	s_nop 0
	v_mfma_f32_16x16x32_bf16 v[100:103], v[100:103], v[8:11], 0
	v_mfma_f32_16x16x32_bf16 v[116:119], v[116:119], v[8:11], 0
	v_mfma_f32_16x16x32_bf16 v[100:103], v[104:107], v[0:3], v[100:103]
	v_mfma_f32_16x16x32_bf16 v[104:107], v[120:123], v[0:3], v[116:119]
	v_mfma_f32_16x16x32_bf16 v[100:103], v[108:111], v[4:7], v[100:103]
	v_mfma_f32_16x16x32_bf16 v[104:107], v[124:127], v[4:7], v[104:107]
	v_mfma_f32_16x16x32_bf16 v[112:115], v[112:115], v[12:15], v[100:103]
	v_mfma_f32_16x16x32_bf16 v[100:103], v[128:131], v[12:15], v[104:107]
	ds_read_b128 v[104:107], v191 offset:0x2200
	ds_read_b128 v[108:111], v191 offset:0x2240
	ds_read_b128 v[116:119], v191 offset:0x2280
	ds_read_b128 v[120:123], v191 offset:0x22c0
	ds_read_b128 v[124:127], v191 offset:0x3300
	ds_read_b128 v[128:131], v191 offset:0x3340
	ds_read_b128 v[132:135], v191 offset:0x3380
	ds_read_b128 v[136:139], v191 offset:0x33c0
	s_waitcnt lgkmcnt(0)
	s_nop 5
	v_mfma_f32_16x16x32_bf16 v[104:107], v[104:107], v[8:11], 0
	s_add_i32 s9, s17, 0xffffff96
	s_cmp_lt_u32 s9, 0xfffffefd
	v_mfma_f32_16x16x32_bf16 v[104:107], v[108:111], v[0:3], v[104:107]
	v_mfma_f32_16x16x32_bf16 v[124:127], v[124:127], v[8:11], 0
	v_mfma_f32_16x16x32_bf16 v[104:107], v[116:119], v[4:7], v[104:107]
	ds_read_b64_tr_b16 v[116:117], v172 offset:36864
	ds_read_b64_tr_b16 v[118:119], v172 offset:45056
	v_mfma_f32_16x16x32_bf16 v[108:111], v[128:131], v[0:3], v[124:127]
	v_mfma_f32_16x16x32_bf16 v[128:131], v[120:123], v[12:15], v[104:107]
	ds_read_b64_tr_b16 v[104:105], v172 offset:53248
	ds_read_b64_tr_b16 v[106:107], v172 offset:61440
	ds_read_b64_tr_b16 v[120:121], v175 offset:36864
	v_mfma_f32_16x16x32_bf16 v[108:111], v[132:135], v[4:7], v[108:111]
	ds_read_b64_tr_b16 v[122:123], v175 offset:45056
	ds_read_b64_tr_b16 v[124:125], v175 offset:53248
	ds_read_b64_tr_b16 v[126:127], v175 offset:61440
	v_mfma_f32_16x16x32_bf16 v[108:111], v[136:139], v[12:15], v[108:111]
	ds_read_b64_tr_b16 v[136:137], v176 offset:36864
	ds_read_b64_tr_b16 v[138:139], v176 offset:45056
	ds_read_b64_tr_b16 v[132:133], v176 offset:53248
	ds_read_b64_tr_b16 v[134:135], v176 offset:61440
	ds_read_b64_tr_b16 v[140:141], v181 offset:36864
	ds_read_b64_tr_b16 v[142:143], v181 offset:45056
	ds_read_b64_tr_b16 v[144:145], v181 offset:53248
	ds_read_b64_tr_b16 v[146:147], v181 offset:61440
	s_cbranch_scc1 .LBB0_258
	v_add_u32_e32 v70, s17, v193
	v_add_u32_e32 v152, 0x80, v70
	v_max_i32_e32 v71, -1, v152
	v_add_u32_e32 v71, 1, v71
	v_med3_i32 v70, v152, 0, v188
	s_add_i32 s9, 0, 0x1a800
	v_min_u32_e32 v71, 0x100, v71
	v_lshl_add_u32 v70, v70, 2, s9
	v_lshl_add_u32 v71, v71, 2, s9
	ds_read_b32 v70, v70
	ds_read_b32 v71, v71
	v_max_i32_e32 v153, -2, v152
	v_add_u32_e32 v153, 2, v153
	v_min_u32_e32 v153, 0x100, v153
	v_lshl_add_u32 v153, v153, 2, s9
	ds_read_b32 v240, v153
	v_max_i32_e32 v153, -3, v152
	s_waitcnt lgkmcnt(1)
	v_pk_add_f32 v[112:113], v[112:113], v[70:71]
	v_max_i32_e32 v70, -16, v152
	v_max_i32_e32 v71, 0xffffffef, v152
	v_add_u32_e32 v153, 3, v153
	v_add_u32_e32 v70, 16, v70
	v_add_u32_e32 v71, 17, v71
	v_min_u32_e32 v153, 0x100, v153
	v_min_u32_e32 v70, 0x100, v70
	v_min_u32_e32 v71, 0x100, v71
	v_lshl_add_u32 v153, v153, 2, s9
	v_lshl_add_u32 v70, v70, 2, s9
	v_lshl_add_u32 v71, v71, 2, s9
	ds_read_b32 v241, v153
	ds_read_b32 v70, v70
	ds_read_b32 v71, v71
	v_max_i32_e32 v153, 0xffffffee, v152
	v_add_u32_e32 v153, 18, v153
	v_min_u32_e32 v153, 0x100, v153
	v_lshl_add_u32 v153, v153, 2, s9
	s_waitcnt lgkmcnt(0)
	v_pk_add_f32 v[100:101], v[100:101], v[70:71]
	v_max_i32_e32 v70, 0xffffffe0, v152
	v_max_i32_e32 v71, 0xffffffdf, v152
	v_add_u32_e32 v70, 32, v70
	v_add_u32_e32 v71, 33, v71
	v_min_u32_e32 v70, 0x100, v70
	v_min_u32_e32 v71, 0x100, v71
	v_lshl_add_u32 v70, v70, 2, s9
	v_lshl_add_u32 v71, v71, 2, s9
	v_pk_add_f32 v[114:115], v[114:115], v[240:241]
	ds_read_b32 v240, v153
	ds_read_b32 v70, v70
	ds_read_b32 v71, v71
	v_max_i32_e32 v153, 0xffffffed, v152
	v_add_u32_e32 v153, 19, v153
	v_min_u32_e32 v153, 0x100, v153
	v_lshl_add_u32 v153, v153, 2, s9
	ds_read_b32 v241, v153
	v_max_i32_e32 v153, 0xffffffde, v152
	v_add_u32_e32 v153, 34, v153
	v_min_u32_e32 v153, 0x100, v153
	v_lshl_add_u32 v153, v153, 2, s9
	s_waitcnt lgkmcnt(0)
	v_pk_add_f32 v[102:103], v[102:103], v[240:241]
	ds_read_b32 v240, v153
	v_max_i32_e32 v153, 0xffffffdd, v152
	v_add_u32_e32 v153, 35, v153
	v_min_u32_e32 v153, 0x100, v153
	v_lshl_add_u32 v153, v153, 2, s9
	ds_read_b32 v241, v153
	v_pk_add_f32 v[128:129], v[128:129], v[70:71]
	v_max_i32_e32 v70, 0xffffffd0, v152
	v_max_i32_e32 v71, 0xffffffcf, v152
	v_max_i32_e32 v153, 0xffffffce, v152
	v_max_i32_e32 v152, 0xffffffcd, v152
	v_add_u32_e32 v70, 48, v70
	v_add_u32_e32 v71, 49, v71
	v_add_u32_e32 v153, 50, v153
	v_add_u32_e32 v152, 51, v152
	v_min_u32_e32 v70, 0x100, v70
	v_min_u32_e32 v71, 0x100, v71
	v_min_u32_e32 v153, 0x100, v153
	v_min_u32_e32 v152, 0x100, v152
	v_lshl_add_u32 v70, v70, 2, s9
	v_lshl_add_u32 v71, v71, 2, s9
	v_lshl_add_u32 v153, v153, 2, s9
	v_lshl_add_u32 v152, v152, 2, s9
	s_waitcnt lgkmcnt(0)
	v_pk_add_f32 v[130:131], v[130:131], v[240:241]
	ds_read_b32 v70, v70
	ds_read_b32 v71, v71
	ds_read_b32 v240, v153
	ds_read_b32 v241, v152
	s_waitcnt lgkmcnt(2)
	v_pk_add_f32 v[108:109], v[108:109], v[70:71]
	s_waitcnt lgkmcnt(0)
	v_pk_add_f32 v[110:111], v[110:111], v[240:241]

.LBB0_260:
	v_sub_f32_e32 v70, v70, v221
	v_mul_f32_e32 v70, 0x3e0293ee, v70
	v_fmamk_f32 v71, v112, 0x3e0293ee, v70
	v_exp_f32_e32 v71, v71
	v_fmamk_f32 v112, v113, 0x3e0293ee, v70
	v_exp_f32_e32 v112, v112
	v_fmamk_f32 v113, v114, 0x3e0293ee, v70
	v_exp_f32_e32 v113, v113
	v_fmamk_f32 v114, v115, 0x3e0293ee, v70
	v_exp_f32_e32 v114, v114
	v_fmamk_f32 v100, v100, 0x3e0293ee, v70
	v_add_f32_e32 v115, 0, v71
	v_exp_f32_e32 v100, v100
	v_fmamk_f32 v101, v101, 0x3e0293ee, v70
	v_add_f32_e32 v115, v112, v115
	v_exp_f32_e32 v101, v101
	v_fmamk_f32 v102, v102, 0x3e0293ee, v70
	v_add_f32_e32 v115, v113, v115
	v_exp_f32_e32 v102, v102
	v_fmamk_f32 v103, v103, 0x3e0293ee, v70
	v_add_f32_e32 v115, v114, v115
	v_exp_f32_e32 v103, v103
	v_fmamk_f32 v128, v128, 0x3e0293ee, v70
	v_add_f32_e32 v115, v100, v115
	v_exp_f32_e32 v128, v128
	v_fmamk_f32 v129, v129, 0x3e0293ee, v70
	v_fmamk_f32 v108, v108, 0x3e0293ee, v70
	v_add_f32_e32 v115, v101, v115
	v_exp_f32_e32 v129, v129
	v_fmamk_f32 v130, v130, 0x3e0293ee, v70
	v_exp_f32_e32 v153, v108
	v_fmamk_f32 v108, v109, 0x3e0293ee, v70
	v_add_f32_e32 v115, v102, v115
	v_exp_f32_e32 v130, v130
	v_fmamk_f32 v131, v131, 0x3e0293ee, v70
	v_exp_f32_e32 v223, v108
	v_fmamk_f32 v108, v110, 0x3e0293ee, v70
	v_fmac_f32_e32 v70, 0x3e0293ee, v111
	v_add_f32_e32 v115, v103, v115
	v_exp_f32_e32 v131, v131
	v_exp_f32_e32 v224, v108
	v_exp_f32_e32 v225, v70
	v_add_f32_e32 v115, v128, v115
	s_waitcnt lgkmcnt(0)
	v_add_f32_e32 v115, v129, v115
	v_add_f32_e32 v115, v130, v115
	s_add_i32 s0, s0, 3
	v_add_f32_e32 v152, v131, v115
	v_cvt_pk_bf16_f32 v108, v71, v112
	v_cvt_pk_bf16_f32 v109, v113, v114
	v_cvt_pk_bf16_f32 v110, v100, v101
	v_cvt_pk_bf16_f32 v111, v102, v103
	v_cvt_pk_bf16_f32 v100, v128, v129
	v_cvt_pk_bf16_f32 v101, v130, v131
	v_cvt_pk_bf16_f32 v102, v153, v223
	v_cvt_pk_bf16_f32 v103, v224, v225
	v_mfma_f32_16x16x32_bf16 v[96:99], v[116:119], v[108:111], v[96:99]
	s_nop 0
	v_mfma_f32_16x16x32_bf16 v[96:99], v[104:107], v[100:103], v[96:99]
	ds_read_b64_tr_b16 v[104:105], v218 offset:36864
	ds_read_b64_tr_b16 v[106:107], v218 offset:45056
	ds_read_b64_tr_b16 v[112:113], v218 offset:53248
	ds_read_b64_tr_b16 v[114:115], v218 offset:61440
	v_mfma_f32_16x16x32_bf16 v[88:91], v[120:123], v[108:111], v[88:91]
	ds_read_b64_tr_b16 v[116:117], v219 offset:36864
	ds_read_b64_tr_b16 v[118:119], v219 offset:45056
	ds_read_b64_tr_b16 v[120:121], v219 offset:53248
	ds_read_b64_tr_b16 v[122:123], v219 offset:61440
	v_mfma_f32_16x16x32_bf16 v[80:83], v[136:139], v[108:111], v[80:83]
	v_mfma_f32_16x16x32_bf16 v[88:91], v[124:127], v[100:103], v[88:91]
	ds_read_b64_tr_b16 v[124:125], v220 offset:36864
	ds_read_b64_tr_b16 v[126:127], v220 offset:45056
	ds_read_b64_tr_b16 v[128:129], v220 offset:53248
	v_mfma_f32_16x16x32_bf16 v[70:73], v[140:143], v[108:111], v[72:75]
	ds_read_b64_tr_b16 v[130:131], v220 offset:61440
	v_mfma_f32_16x16x32_bf16 v[80:83], v[132:135], v[100:103], v[80:83]
	ds_read_b64_tr_b16 v[132:133], v171 offset:36864
	ds_read_b64_tr_b16 v[134:135], v171 offset:45056
	ds_read_b64_tr_b16 v[136:137], v171 offset:53248
	v_mfma_f32_16x16x32_bf16 v[72:75], v[144:147], v[100:103], v[70:73]
	ds_read_b64_tr_b16 v[138:139], v171 offset:61440
	s_waitcnt lgkmcnt(0)
	v_mfma_f32_16x16x32_bf16 v[56:59], v[104:107], v[108:111], v[56:59]
	ds_read_b64_tr_b16 v[104:105], v172 offset:37120
	ds_read_b64_tr_b16 v[106:107], v172 offset:45312
	v_mfma_f32_16x16x32_bf16 v[48:51], v[116:119], v[108:111], v[48:51]
	v_mfma_f32_16x16x32_bf16 v[56:59], v[112:115], v[100:103], v[56:59]
	ds_read_b64_tr_b16 v[112:113], v172 offset:53504
	ds_read_b64_tr_b16 v[114:115], v172 offset:61696
	ds_read_b64_tr_b16 v[116:117], v175 offset:37120
	ds_read_b64_tr_b16 v[118:119], v175 offset:45312
	v_mfma_f32_16x16x32_bf16 v[40:43], v[124:127], v[108:111], v[40:43]
	v_mfma_f32_16x16x32_bf16 v[48:51], v[120:123], v[100:103], v[48:51]
	ds_read_b64_tr_b16 v[120:121], v175 offset:53504
	ds_read_b64_tr_b16 v[122:123], v175 offset:61696
	ds_read_b64_tr_b16 v[124:125], v176 offset:37120
	ds_read_b64_tr_b16 v[126:127], v176 offset:45312
	v_mfma_f32_16x16x32_bf16 v[32:35], v[132:135], v[108:111], v[32:35]
	v_mfma_f32_16x16x32_bf16 v[40:43], v[128:131], v[100:103], v[40:43]
	ds_read_b64_tr_b16 v[128:129], v176 offset:53504
	ds_read_b64_tr_b16 v[130:131], v176 offset:61696
	ds_read_b64_tr_b16 v[132:133], v181 offset:37120
	ds_read_b64_tr_b16 v[134:135], v181 offset:45312
	v_mfma_f32_16x16x32_bf16 v[32:35], v[136:139], v[100:103], v[32:35]
	ds_read_b64_tr_b16 v[136:137], v181 offset:53504
	ds_read_b64_tr_b16 v[138:139], v181 offset:61696
	s_waitcnt lgkmcnt(0)
	v_mfma_f32_16x16x32_bf16 v[92:95], v[104:107], v[108:111], v[92:95]
	ds_read_b64_tr_b16 v[104:105], v218 offset:37120
	ds_read_b64_tr_b16 v[106:107], v218 offset:45312
	v_mfma_f32_16x16x32_bf16 v[84:87], v[116:119], v[108:111], v[84:87]
	v_mfma_f32_16x16x32_bf16 v[92:95], v[112:115], v[100:103], v[92:95]
	ds_read_b64_tr_b16 v[112:113], v218 offset:53504
	ds_read_b64_tr_b16 v[114:115], v218 offset:61696
	ds_read_b64_tr_b16 v[116:117], v219 offset:37120
	ds_read_b64_tr_b16 v[118:119], v219 offset:45312
	v_mfma_f32_16x16x32_bf16 v[76:79], v[124:127], v[108:111], v[76:79]
	v_mfma_f32_16x16x32_bf16 v[84:87], v[120:123], v[100:103], v[84:87]
	ds_read_b64_tr_b16 v[120:121], v219 offset:53504
	ds_read_b64_tr_b16 v[122:123], v219 offset:61696
	ds_read_b64_tr_b16 v[124:125], v220 offset:37120
	ds_read_b64_tr_b16 v[126:127], v220 offset:45312
	v_mfma_f32_16x16x32_bf16 v[66:69], v[132:135], v[108:111], v[66:69]
	v_mfma_f32_16x16x32_bf16 v[76:79], v[128:131], v[100:103], v[76:79]
	ds_read_b64_tr_b16 v[128:129], v220 offset:53504
	ds_read_b64_tr_b16 v[130:131], v220 offset:61696
	ds_read_b64_tr_b16 v[132:133], v171 offset:37120
	ds_read_b64_tr_b16 v[134:135], v171 offset:45312
	v_mfma_f32_16x16x32_bf16 v[68:71], v[136:139], v[100:103], v[66:69]
	ds_read_b64_tr_b16 v[136:137], v171 offset:53504
	ds_read_b64_tr_b16 v[138:139], v171 offset:61696
	s_waitcnt lgkmcnt(0)
	v_mfma_f32_16x16x32_bf16 v[60:63], v[104:107], v[108:111], v[60:63]
	v_mfma_f32_16x16x32_bf16 v[52:55], v[116:119], v[108:111], v[52:55]
	v_mfma_f32_16x16x32_bf16 v[44:47], v[124:127], v[108:111], v[44:47]
	v_mfma_f32_16x16x32_bf16 v[36:39], v[132:135], v[108:111], v[36:39]
	v_mfma_f32_16x16x32_bf16 v[60:63], v[112:115], v[100:103], v[60:63]
	v_mfma_f32_16x16x32_bf16 v[52:55], v[120:123], v[100:103], v[52:55]
	v_mfma_f32_16x16x32_bf16 v[44:47], v[128:131], v[100:103], v[44:47]
	v_mfma_f32_16x16x32_bf16 v[36:39], v[136:139], v[100:103], v[36:39]
	s_waitcnt vmcnt(6)
	ds_write_b128 v166, v[24:27]
	ds_write_b128 v167, v[28:31]
	v_add_f32_e32 v24, v153, v152
	v_add_f32_e32 v24, v223, v24
	v_add_f32_e32 v24, v224, v24
	v_add_f32_e32 v66, v225, v24
	ds_write_b128 v169, v[206:209] offset:0
	ds_write_b128 v169, v[210:213] offset:8192
	ds_write_b128 v169, v[214:217] offset:16384
	ds_write_b128 v169, v[248:251] offset:24576
	s_min_u32 s0, s0, 28
	s_waitcnt lgkmcnt(0)
	s_barrier
	s_lshl_b32 s0, s0, 6
	s_addk_i32 s0, 0xc0
	s_mul_i32 s29, s0, 0xa080
	s_add_u32 s72, s24, s29
	s_addc_u32 s73, s25, 0
	s_add_u32 s74, s26, s29
	s_addc_u32 s75, s27, 0
	s_add_u32 s76, s74, 0xa0800
	s_addc_u32 s77, s75, 0
	s_add_u32 s78, s76, 0xa0800
	s_addc_u32 s79, s77, 0
	s_add_u32 s80, s78, 0xa0800
	s_addc_u32 s81, s79, 0
	s_addk_i32 s17, 0x80
	s_cmp_lt_u32 s8, 30
	v_add_f32_e32 v222, v222, v66
	s_cbranch_scc0 .LBB0_248
	s_mov_b32 s0, s8
	s_branch .LBB0_252
